# SwiGLU epilogue reads row rstd from a per-phase LDS table (filled once at phase entry) instead of 16 global loads + 8 rsq per unit
# speedup vs baseline: 1.0085x; 1.0085x over previous
; #define PG8_STAGE(bufoff, gbase, voff) do { _Pragma("unroll") for (int _i = 0; _i < 2; ++_i) \
;         __builtin_amdgcn_global_load_lds((const unsigned*)((const char*)(gbase) + (voff)[_i]), (LAS unsigned*)(lds + (bufoff) + ldsw + _i * 8192), 16, 0, 0); } while (0)
; #define PG8_WAIT_V(n) asm volatile("s_waitcnt vmcnt(" #n ")" ::: "memory")
; #define PG8_BAR __builtin_amdgcn_s_barrier()
;     __device__ __forceinline__ void operator()(const f32x4 (&acc)[2][2][4][2], const Unit& u, int wr, int wc, int fr, int fq) const {
;     ...
;             for (int m = 0; m < 4; ++m) { const float* p_ = st2 + (size_t)(row0 + ai * HALF + m * 16) * 8; pa[ai][m] = *(const f32x4*)p_; pb[ai][m] = *(const f32x4*)(p_ + 4); }
;           __builtin_amdgcn_sched_barrier(0);
; #pragma unroll
;           for (int ai = 0; ai < 2; ++ai)
; #pragma unroll
;             for (int m = 0; m < 4; ++m) { const f32x4 t_ = pa[ai][m] + pb[ai][m]; rs8[ai][m] = __builtin_amdgcn_rsqf(((t_[0] + t_[1]) + (t_[2] + t_[3])) * (1.0f / (float)D) + 1e-6f); }
; template <class Epi, class Sched>
; __device__ __forceinline__ void gemm_phase(LAS unsigned char* lds, const Gemm g, const Sched& S, const Epi& E) {
;     ...
;     const char* cA = (const char*)g.A + (size_t)cur.pm * tstepA + (size_t)cur.ka * 2; const char* cB = (const char*)g.Bt + (size_t)cur.pn * tstepB;
;     S.a_ready(cur);
;     PG8_STAGE(PG8_SB(0, 0), cB, voffB); PG8_STAGE(PG8_SB(0, 1), cB + hstepB, voffB); PG8_STAGE(PG8_SA(0, 0), cA, voffA); PG8_STAGE(PG8_SA(0, 1), cA + hstepA, voffA);
;     if (wr == 1) PG8_BAR;
;     PG8_WAIT_V(2); PG8_BAR;
;     PG8_STAGE(PG8_SB(1, 0), cB + kstep, voffB); PG8_STAGE(PG8_SA(1, 0), cA + kstep, voffA); PG8_STAGE(PG8_SB(1, 1), cB + hstepB + kstep, voffB);
;     PG8_WAIT_V(6); PG8_BAR;
.LBB0_131:
	s_add_u32 s12, s14, 0xd000000
	s_addc_u32 s13, s15, 0
	s_add_u32 s14, s14, 0x100000
	s_addc_u32 s15, s15, 0
	s_lshl_b32 s18, s18, 5
	s_and_b32 s21, s18, 0x60
	s_add_i32 m0, s46, 0x18000
	v_lshl_add_u64 v[12:13], v[12:13], 0, s[36:37]
	s_lshl_b32 s20, s17, 13
	s_lshl_b32 s22, s21, 7
	s_waitcnt vmcnt(2)
	s_barrier
	global_load_lds_dwordx4 v[12:13], off
	v_lshl_add_u64 v[10:11], v[10:11], 0, s[36:37]
	s_add_i32 m0, s46, 0x1a000
	s_add_i32 s50, s46, 0x8000
	s_add_i32 s51, s46, 0xa000
	global_load_lds_dwordx4 v[10:11], off
	v_lshl_add_u64 v[6:7], v[6:7], 0, s[36:37]
	s_mov_b32 m0, s50
	s_add_u32 s18, s28, 0x80080
	global_load_lds_dwordx4 v[6:7], off
	v_lshl_add_u64 v[6:7], v[8:9], 0, s[36:37]
	s_mov_b32 m0, s51
	s_addc_u32 s19, s29, 0
	global_load_lds_dwordx4 v[6:7], off
	s_add_i32 m0, s46, 0x1c000
	v_lshl_add_u64 v[6:7], s[18:19], 0, v[4:5]
	global_load_lds_dwordx4 v[6:7], off
	v_lshl_add_u64 v[6:7], s[18:19], 0, v[2:3]
	s_add_i32 m0, s46, 0x1e000
	v_readlane_b32 s18, v253, 57
	global_load_lds_dwordx4 v[6:7], off
	v_lshrrev_b32_e32 v7, 1, v14
	v_and_b32_e32 v7, 24, v7
	v_and_b32_e32 v6, 15, v14
	v_lshlrev_b32_e32 v8, 1, v7
	v_lshl_or_b32 v158, s17, 6, v6
	v_lshl_or_b32 v6, v6, 6, v8
	v_lshlrev_b32_e32 v8, 2, v14
	v_and_b32_e32 v8, 32, v8
	v_bitop3_b32 v9, v6, s20, v8 bitop3:0xde
	v_bitop3_b32 v159, v6, s22, v8 bitop3:0xde
	v_lshlrev_b32_e32 v6, 15, v19
	v_and_b32_e32 v6, 0xffff0000, v6
	v_or_b32_e32 v160, s21, v7
	v_lshl_add_u32 v6, v18, 12, v6
	v_and_b32_e32 v7, 1, v19
	v_lshl_or_b32 v6, v7, 6, v6
	v_lshl_add_u32 v138, v20, 1, v6
	v_lshlrev_b32_e32 v6, 15, v15
	v_and_b32_e32 v6, 0xffff0000, v6
	s_waitcnt vmcnt(6)
	v_lshl_add_u32 v6, v16, 12, v6
	v_and_b32_e32 v7, 1, v15
	v_readlane_b32 s19, v253, 58
	s_cmpk_lt_u32 s16, 0x100
	v_lshl_or_b32 v6, v7, 6, v6
	s_mov_b32 s53, s18
	v_readlane_b32 s18, v253, 53
	s_cselect_b64 s[16:17], -1, 0
	v_mov_b32_e32 v139, v5
	v_lshl_add_u32 v140, v17, 1, v6
	v_mov_b32_e32 v141, v5
	s_mov_b32 s52, 0
	v_add_u32_e32 v161, 0, v9
	s_mov_b32 s54, s18
	v_cmp_gt_u32_e32 vcc, 0x100, v14
	s_and_saveexec_b64 s[100:101], vcc
	s_cbranch_execz .Lmy_rsfill_done
	v_lshl_add_u32 v162, s54, 8, v14
	v_lshlrev_b32_e32 v162, 5, v162
	global_load_dwordx4 v[164:167], v162, s[14:15]
	global_load_dwordx4 v[168:171], v162, s[14:15] offset:16
	v_lshlrev_b32_e32 v163, 2, v14
	v_add_u32_e32 v163, 0x21800, v163
	s_waitcnt vmcnt(0)
	v_add_f32_e32 v164, v164, v168
	v_add_f32_e32 v165, v165, v169
	v_add_f32_e32 v166, v166, v170
	v_add_f32_e32 v167, v167, v171
	v_add_f32_e32 v164, v165, v164
	v_add_f32_e32 v166, v166, v167
	v_add_f32_e32 v164, v164, v166
	v_fmamk_f32 v164, v164, 0x3a000000, v1
	v_rsq_f32_e32 v164, v164
	s_nop 0
	ds_write_b32 v163, v164
.Lmy_rsfill_done:
	s_or_b64 exec, exec, s[100:101]
	s_mov_b32 s100, s54
	s_waitcnt lgkmcnt(0)
	s_barrier
	v_readlane_b32 s19, v253, 54
	s_branch .LBB0_134

;     __device__ __forceinline__ void operator()(const f32x4 (&acc)[2][2][4][2], const Unit& u, int wr, int wc, int fr, int fq) const {
;         const int row0 = u.pm * BM + wr * 64 + fr, col0 = u.pn * HALF + wc * 32 + 8 * fq;
;         float rs8[2][4];
;         { f32x4 pa[2][4], pb[2][4];
; #pragma unroll
;           for (int ai = 0; ai < 2; ++ai)
; #pragma unroll
;             for (int m = 0; m < 4; ++m) { const float* p_ = st2 + (size_t)(row0 + ai * HALF + m * 16) * 8; pa[ai][m] = *(const f32x4*)p_; pb[ai][m] = *(const f32x4*)(p_ + 4); }
;           __builtin_amdgcn_sched_barrier(0);
; #pragma unroll
;           for (int ai = 0; ai < 2; ++ai)
; #pragma unroll
;             for (int m = 0; m < 4; ++m) { const f32x4 t_ = pa[ai][m] + pb[ai][m]; rs8[ai][m] = __builtin_amdgcn_rsqf(((t_[0] + t_[1]) + (t_[2] + t_[3])) * (1.0f / (float)D) + 1e-6f); }
;           __builtin_amdgcn_sched_barrier(0); }
.LBB0_140:
	v_lshl_add_u32 v156, s54, 8, v158
	s_cmp_lg_u32 s54, s100
	s_cbranch_scc1 .Lmy_sw_slow
	v_lshlrev_b32_e32 v162, 2, v158
	v_add_u32_e32 v162, 0x21800, v162
	ds_read_b32 v147, v162
	ds_read_b32 v149, v162 offset:64
	ds_read_b32 v151, v162 offset:128
	ds_read_b32 v153, v162 offset:192
	ds_read_b32 v155, v162 offset:512
	ds_read_b32 v157, v162 offset:576
	ds_read_b32 v145, v162 offset:640
	ds_read_b32 v143, v162 offset:704
	v_or_b32_e32 v154, 16, v156
	v_or_b32_e32 v152, 32, v156
	v_or_b32_e32 v150, 48, v156
	v_add_u32_e32 v148, 0x80, v156
	v_add_u32_e32 v146, 0x90, v156
	v_add_u32_e32 v144, 0xa0, v156
	v_add_u32_e32 v142, 0xb0, v156
	s_waitcnt lgkmcnt(0)
	s_branch .Lmy_sw_join
.Lmy_sw_slow:
	v_ashrrev_i32_e32 v157, 31, v156
	v_lshlrev_b64 v[142:143], 5, v[156:157]
	v_or_b32_e32 v154, 16, v156
	v_lshl_add_u64 v[142:143], s[14:15], 0, v[142:143]
	v_ashrrev_i32_e32 v155, 31, v154
	global_load_dwordx4 v[162:165], v[142:143], off
	global_load_dwordx4 v[166:169], v[142:143], off offset:16
	v_lshlrev_b64 v[142:143], 5, v[154:155]
	v_or_b32_e32 v152, 32, v156
	v_lshl_add_u64 v[142:143], s[14:15], 0, v[142:143]
	v_ashrrev_i32_e32 v153, 31, v152
	global_load_dwordx4 v[170:173], v[142:143], off
	global_load_dwordx4 v[174:177], v[142:143], off offset:16
	v_lshlrev_b64 v[142:143], 5, v[152:153]
	v_or_b32_e32 v150, 48, v156
	v_lshl_add_u64 v[142:143], s[14:15], 0, v[142:143]
	v_ashrrev_i32_e32 v151, 31, v150
	global_load_dwordx4 v[178:181], v[142:143], off
	global_load_dwordx4 v[182:185], v[142:143], off offset:16
	v_lshlrev_b64 v[142:143], 5, v[150:151]
	v_add_u32_e32 v148, 0x80, v156
	v_lshl_add_u64 v[142:143], s[14:15], 0, v[142:143]
	v_ashrrev_i32_e32 v149, 31, v148
	global_load_dwordx4 v[186:189], v[142:143], off
	global_load_dwordx4 v[190:193], v[142:143], off offset:16
	v_lshlrev_b64 v[142:143], 5, v[148:149]
	v_add_u32_e32 v146, 0x90, v156
	v_lshl_add_u64 v[142:143], s[14:15], 0, v[142:143]
	v_ashrrev_i32_e32 v147, 31, v146
	global_load_dwordx4 v[194:197], v[142:143], off
	global_load_dwordx4 v[212:215], v[142:143], off offset:16
	v_lshlrev_b64 v[142:143], 5, v[146:147]
	v_add_u32_e32 v144, 0xa0, v156
	v_lshl_add_u64 v[142:143], s[14:15], 0, v[142:143]
	v_ashrrev_i32_e32 v145, 31, v144
	global_load_dwordx4 v[216:219], v[142:143], off
	global_load_dwordx4 v[220:223], v[142:143], off offset:16
	v_lshlrev_b64 v[142:143], 5, v[144:145]
	v_lshl_add_u64 v[142:143], s[14:15], 0, v[142:143]
	global_load_dwordx4 v[224:227], v[142:143], off
	global_load_dwordx4 v[228:231], v[142:143], off offset:16
	v_add_u32_e32 v142, 0xb0, v156
	v_ashrrev_i32_e32 v143, 31, v142
	v_lshlrev_b64 v[236:237], 5, v[142:143]
	v_lshl_add_u64 v[236:237], s[14:15], 0, v[236:237]
	global_load_dwordx4 v[240:243], v[236:237], off
	global_load_dwordx4 v[244:247], v[236:237], off offset:16
	s_waitcnt vmcnt(0)
	v_pk_add_f32 v[164:165], v[164:165], v[168:169]
	v_pk_add_f32 v[162:163], v[162:163], v[166:167]
	s_nop 0
	v_pk_mov_b32 v[166:167], v[162:163], v[164:165] op_sel:[1,0]
	v_mov_b32_e32 v163, v165
	v_pk_add_f32 v[162:163], v[166:167], v[162:163]
	v_pk_add_f32 v[164:165], v[170:171], v[174:175]
	v_add_f32_e32 v143, v162, v163
	v_pk_add_f32 v[162:163], v[172:173], v[176:177]
	v_fmamk_f32 v143, v143, 0x3a000000, v1
	v_pk_mov_b32 v[166:167], v[164:165], v[162:163] op_sel:[1,0]
	v_mov_b32_e32 v165, v163
	v_pk_add_f32 v[162:163], v[166:167], v[164:165]
	v_rsq_f32_e32 v147, v143
	v_add_f32_e32 v143, v162, v163
	v_pk_add_f32 v[162:163], v[180:181], v[184:185]
	v_pk_add_f32 v[164:165], v[178:179], v[182:183]
	v_fmamk_f32 v143, v143, 0x3a000000, v1
	v_pk_mov_b32 v[166:167], v[164:165], v[162:163] op_sel:[1,0]
	v_mov_b32_e32 v165, v163
	v_pk_add_f32 v[162:163], v[166:167], v[164:165]
	v_rsq_f32_e32 v149, v143
	v_add_f32_e32 v143, v162, v163
	v_pk_add_f32 v[162:163], v[188:189], v[192:193]
	v_pk_add_f32 v[164:165], v[186:187], v[190:191]
	v_fmamk_f32 v143, v143, 0x3a000000, v1
	v_pk_mov_b32 v[166:167], v[164:165], v[162:163] op_sel:[1,0]
	v_mov_b32_e32 v165, v163
	v_pk_add_f32 v[162:163], v[166:167], v[164:165]
	v_rsq_f32_e32 v151, v143
	v_add_f32_e32 v143, v162, v163
	v_pk_add_f32 v[162:163], v[196:197], v[214:215]
	v_pk_add_f32 v[164:165], v[194:195], v[212:213]
	v_fmamk_f32 v143, v143, 0x3a000000, v1
	v_pk_mov_b32 v[166:167], v[164:165], v[162:163] op_sel:[1,0]
	v_mov_b32_e32 v165, v163
	v_pk_add_f32 v[162:163], v[166:167], v[164:165]
	v_rsq_f32_e32 v153, v143
	v_add_f32_e32 v143, v162, v163
	v_pk_add_f32 v[162:163], v[218:219], v[222:223]
	v_pk_add_f32 v[164:165], v[216:217], v[220:221]
	v_fmamk_f32 v143, v143, 0x3a000000, v1
	v_pk_mov_b32 v[166:167], v[164:165], v[162:163] op_sel:[1,0]
	v_mov_b32_e32 v165, v163
	v_pk_add_f32 v[162:163], v[166:167], v[164:165]
	v_rsq_f32_e32 v155, v143
	v_add_f32_e32 v143, v162, v163
	v_pk_add_f32 v[162:163], v[226:227], v[230:231]
	v_pk_add_f32 v[164:165], v[224:225], v[228:229]
	v_fmamk_f32 v143, v143, 0x3a000000, v1
	v_pk_mov_b32 v[166:167], v[164:165], v[162:163] op_sel:[1,0]
	v_mov_b32_e32 v165, v163
	v_pk_add_f32 v[162:163], v[166:167], v[164:165]
	v_rsq_f32_e32 v157, v143
	v_add_f32_e32 v143, v162, v163
	v_pk_add_f32 v[162:163], v[242:243], v[246:247]
	v_pk_add_f32 v[164:165], v[240:241], v[244:245]
	v_fmamk_f32 v143, v143, 0x3a000000, v1
	v_pk_mov_b32 v[166:167], v[164:165], v[162:163] op_sel:[1,0]
	v_mov_b32_e32 v165, v163
	v_pk_add_f32 v[162:163], v[166:167], v[164:165]
	v_rsq_f32_e32 v145, v143
	v_add_f32_e32 v143, v162, v163
	v_fmamk_f32 v143, v143, 0x3a000000, v1
	v_rsq_f32_e32 v143, v143
; __device__ __forceinline__ unsigned pk2(float lo, float hi) { const f32x2 v = {lo, hi}; return __builtin_bit_cast(unsigned, __builtin_convertvector(v, bf16x2_t)); }
;     __device__ __forceinline__ void operator()(const f32x4 (&acc)[2][2][4][2], const Unit& u, int wr, int wc, int fr, int fq) const {
;     ...
; #pragma unroll
;         for (int ai = 0; ai < 2; ++ai)
; #pragma unroll
;             for (int m = 0; m < 4; ++m) {
;                 const float rs = rs8[ai][m], nrs = -1.44269504089f * rs;
;                 u32x4 w;
; #pragma unroll
;                 for (int n = 0; n < 2; ++n) { const f32x4 gq = acc[ai][0][m][n], uq = acc[ai][1][m][n];
; #pragma unroll
;                     for (int h = 0; h < 2; ++h) { const f32x2 gv = (f32x2){gq[2 * h], gq[2 * h + 1]}, uv = (f32x2){uq[2 * h], uq[2 * h + 1]};
;                         const f32x2 ea = gv * nrs; f32x2 e; e.x = __builtin_amdgcn_exp2f(ea.x); e.y = __builtin_amdgcn_exp2f(ea.y);
;                         const f32x2 d = e + 1.0f; f32x2 rc; rc.x = __builtin_amdgcn_rcpf(d.x); rc.y = __builtin_amdgcn_rcpf(d.y);
;                         const f32x2 o = (gv * uv) * (rc * (rs * rs));
;                         w[2 * n + h] = pk2(o.x, o.y); } }
;                 *(u32x4*)(O + (size_t)(row0 + ai * HALF + m * 16) * ldc + col0) = w; }
.Lmy_sw_join:
	v_lshl_or_b32 v162, s53, 7, v160
	v_mul_f32_e32 v164, 0xbfb8aa3b, v147
	v_pk_mul_f32 v[166:167], v[130:131], v[164:165] op_sel_hi:[1,0]
	v_pk_mul_f32 v[126:127], v[130:131], v[126:127]
	v_exp_f32_e32 v166, v166
	v_exp_f32_e32 v167, v167
	v_pk_mul_f32 v[130:131], v[132:133], v[164:165] op_sel_hi:[1,0]
	v_mul_f32_e32 v168, v147, v147
	v_exp_f32_e32 v130, v130
	v_exp_f32_e32 v131, v131
	v_pk_add_f32 v[166:167], v[166:167], 1.0 op_sel_hi:[1,0]
	v_pk_mul_f32 v[128:129], v[132:133], v[128:129]
	v_rcp_f32_e32 v166, v166
	v_rcp_f32_e32 v167, v167
	v_pk_add_f32 v[130:131], v[130:131], 1.0 op_sel_hi:[1,0]
	v_pk_mul_f32 v[118:119], v[122:123], v[118:119]
	v_rcp_f32_e32 v130, v130
	v_rcp_f32_e32 v131, v131
	v_pk_mul_f32 v[132:133], v[168:169], v[166:167] op_sel_hi:[0,1]
	v_pk_mul_f32 v[126:127], v[126:127], v[132:133]
	v_pk_mul_f32 v[132:133], v[122:123], v[164:165] op_sel_hi:[1,0]
	v_pk_mul_f32 v[130:131], v[168:169], v[130:131] op_sel_hi:[0,1]
	v_exp_f32_e32 v132, v132
	v_exp_f32_e32 v133, v133
	v_pk_mul_f32 v[128:129], v[128:129], v[130:131]
	v_pk_mul_f32 v[130:131], v[124:125], v[164:165] op_sel_hi:[1,0]
	v_cvt_pk_bf16_f32 v126, v126, v127
	v_exp_f32_e32 v130, v130
	v_exp_f32_e32 v131, v131
	v_cvt_pk_bf16_f32 v127, v128, v129
	v_pk_add_f32 v[128:129], v[132:133], 1.0 op_sel_hi:[1,0]
	v_pk_mul_f32 v[120:121], v[124:125], v[120:121]
	v_rcp_f32_e32 v128, v128
	v_rcp_f32_e32 v129, v129
	v_pk_add_f32 v[122:123], v[130:131], 1.0 op_sel_hi:[1,0]
	v_ashrrev_i32_e32 v163, 31, v162
	v_rcp_f32_e32 v122, v122
	v_rcp_f32_e32 v123, v123
	v_pk_mul_f32 v[124:125], v[168:169], v[128:129] op_sel_hi:[0,1]
	v_pk_mul_f32 v[118:119], v[118:119], v[124:125]
	v_mul_f32_e32 v124, 0xbfb8aa3b, v149
	v_cvt_pk_bf16_f32 v128, v118, v119
	v_pk_mul_f32 v[118:119], v[168:169], v[122:123] op_sel_hi:[0,1]
	v_pk_mul_f32 v[130:131], v[114:115], v[124:125] op_sel_hi:[1,0]
	v_pk_mul_f32 v[118:119], v[120:121], v[118:119]
	v_exp_f32_e32 v130, v130
	v_exp_f32_e32 v131, v131
	v_cvt_pk_bf16_f32 v129, v118, v119
	v_mov_b64_e32 v[118:119], s[12:13]
	v_pk_mul_f32 v[110:111], v[114:115], v[110:111]
	v_pk_mul_f32 v[114:115], v[116:117], v[124:125] op_sel_hi:[1,0]
	v_mad_i64_i32 v[122:123], s[26:27], v156, s1, v[118:119]
	v_lshlrev_b64 v[120:121], 1, v[162:163]
	v_exp_f32_e32 v114, v114
	v_exp_f32_e32 v115, v115
	v_lshl_add_u64 v[122:123], v[122:123], 0, v[120:121]
	global_store_dwordx4 v[122:123], v[126:129], off
	v_mul_f32_e32 v122, v149, v149
	v_pk_add_f32 v[114:115], v[114:115], 1.0 op_sel_hi:[1,0]
	v_pk_add_f32 v[126:127], v[130:131], 1.0 op_sel_hi:[1,0]
	v_rcp_f32_e32 v114, v114
	v_rcp_f32_e32 v126, v126
	v_rcp_f32_e32 v127, v127
	v_rcp_f32_e32 v115, v115
	v_pk_mul_f32 v[112:113], v[116:117], v[112:113]
	v_pk_mul_f32 v[102:103], v[106:107], v[102:103]
	v_pk_mul_f32 v[116:117], v[122:123], v[126:127] op_sel_hi:[0,1]
	v_pk_mul_f32 v[110:111], v[110:111], v[116:117]
	v_pk_mul_f32 v[116:117], v[106:107], v[124:125] op_sel_hi:[1,0]
	v_pk_mul_f32 v[114:115], v[122:123], v[114:115] op_sel_hi:[0,1]
	v_exp_f32_e32 v116, v116
	v_exp_f32_e32 v117, v117
	v_pk_mul_f32 v[112:113], v[112:113], v[114:115]
	v_pk_mul_f32 v[114:115], v[108:109], v[124:125] op_sel_hi:[1,0]
	v_cvt_pk_bf16_f32 v110, v110, v111
	v_exp_f32_e32 v114, v114
	v_exp_f32_e32 v115, v115
	v_cvt_pk_bf16_f32 v111, v112, v113
	v_pk_add_f32 v[112:113], v[116:117], 1.0 op_sel_hi:[1,0]
	v_pk_mul_f32 v[104:105], v[108:109], v[104:105]
	v_rcp_f32_e32 v112, v112
	v_rcp_f32_e32 v113, v113
	v_pk_add_f32 v[106:107], v[114:115], 1.0 op_sel_hi:[1,0]
	v_pk_mul_f32 v[94:95], v[98:99], v[94:95]
	v_rcp_f32_e32 v106, v106
	v_rcp_f32_e32 v107, v107
	v_pk_mul_f32 v[108:109], v[122:123], v[112:113] op_sel_hi:[0,1]
	v_pk_mul_f32 v[102:103], v[102:103], v[108:109]
	v_pk_mul_f32 v[96:97], v[100:101], v[96:97]
	v_cvt_pk_bf16_f32 v112, v102, v103
	v_pk_mul_f32 v[102:103], v[122:123], v[106:107] op_sel_hi:[0,1]
	v_pk_mul_f32 v[102:103], v[104:105], v[102:103]
	v_mul_f32_e32 v104, 0xbfb8aa3b, v151
	v_pk_mul_f32 v[106:107], v[98:99], v[104:105] op_sel_hi:[1,0]
	v_pk_mul_f32 v[98:99], v[100:101], v[104:105] op_sel_hi:[1,0]
	v_exp_f32_e32 v106, v106
	v_exp_f32_e32 v107, v107
	v_exp_f32_e32 v98, v98
	v_exp_f32_e32 v99, v99
	v_cvt_pk_bf16_f32 v113, v102, v103
	v_pk_add_f32 v[106:107], v[106:107], 1.0 op_sel_hi:[1,0]
	v_mad_i64_i32 v[102:103], s[26:27], v154, s1, v[118:119]
	v_rcp_f32_e32 v106, v106
	v_rcp_f32_e32 v107, v107
	v_pk_add_f32 v[98:99], v[98:99], 1.0 op_sel_hi:[1,0]
	v_lshl_add_u64 v[102:103], v[102:103], 0, v[120:121]
	v_rcp_f32_e32 v98, v98
	v_rcp_f32_e32 v99, v99
	global_store_dwordx4 v[102:103], v[110:113], off
	v_mul_f32_e32 v102, v151, v151
	v_pk_mul_f32 v[100:101], v[102:103], v[106:107] op_sel_hi:[0,1]
	v_pk_mul_f32 v[94:95], v[94:95], v[100:101]
	v_pk_mul_f32 v[100:101], v[90:91], v[104:105] op_sel_hi:[1,0]
	v_pk_mul_f32 v[98:99], v[102:103], v[98:99] op_sel_hi:[0,1]
	v_exp_f32_e32 v100, v100
	v_exp_f32_e32 v101, v101
	v_pk_mul_f32 v[96:97], v[96:97], v[98:99]
	v_pk_mul_f32 v[98:99], v[92:93], v[104:105] op_sel_hi:[1,0]
	v_cvt_pk_bf16_f32 v94, v94, v95
	v_exp_f32_e32 v98, v98
	v_exp_f32_e32 v99, v99
	v_cvt_pk_bf16_f32 v95, v96, v97
	v_pk_add_f32 v[96:97], v[100:101], 1.0 op_sel_hi:[1,0]
	v_pk_mul_f32 v[86:87], v[90:91], v[86:87]
	v_rcp_f32_e32 v96, v96
	v_rcp_f32_e32 v97, v97
	v_pk_add_f32 v[90:91], v[98:99], 1.0 op_sel_hi:[1,0]
	v_pk_mul_f32 v[88:89], v[92:93], v[88:89]
	v_rcp_f32_e32 v90, v90
	v_rcp_f32_e32 v91, v91
	v_pk_mul_f32 v[92:93], v[102:103], v[96:97] op_sel_hi:[0,1]
	v_pk_mul_f32 v[86:87], v[86:87], v[92:93]
	v_pk_mul_f32 v[78:79], v[82:83], v[78:79]
	v_cvt_pk_bf16_f32 v96, v86, v87
	v_pk_mul_f32 v[86:87], v[102:103], v[90:91] op_sel_hi:[0,1]
; __device__ __forceinline__ unsigned pk2(float lo, float hi) { const f32x2 v = {lo, hi}; return __builtin_bit_cast(unsigned, __builtin_convertvector(v, bf16x2_t)); }
;     __device__ __forceinline__ void operator()(const f32x4 (&acc)[2][2][4][2], const Unit& u, int wr, int wc, int fr, int fq) const {
;     ...
; #pragma unroll
;         for (int ai = 0; ai < 2; ++ai)
; #pragma unroll
;             for (int m = 0; m < 4; ++m) {
;                 const float rs = rs8[ai][m], nrs = -1.44269504089f * rs;
;                 u32x4 w;
; #pragma unroll
;                 for (int n = 0; n < 2; ++n) { const f32x4 gq = acc[ai][0][m][n], uq = acc[ai][1][m][n];
; #pragma unroll
;                     for (int h = 0; h < 2; ++h) { const f32x2 gv = (f32x2){gq[2 * h], gq[2 * h + 1]}, uv = (f32x2){uq[2 * h], uq[2 * h + 1]};
;                         const f32x2 ea = gv * nrs; f32x2 e; e.x = __builtin_amdgcn_exp2f(ea.x); e.y = __builtin_amdgcn_exp2f(ea.y);
;                         const f32x2 d = e + 1.0f; f32x2 rc; rc.x = __builtin_amdgcn_rcpf(d.x); rc.y = __builtin_amdgcn_rcpf(d.y);
;                         const f32x2 o = (gv * uv) * (rc * (rs * rs));
;                         w[2 * n + h] = pk2(o.x, o.y); } }
;                 *(u32x4*)(O + (size_t)(row0 + ai * HALF + m * 16) * ldc + col0) = w; }
	v_pk_mul_f32 v[86:87], v[88:89], v[86:87]
	v_mul_f32_e32 v88, 0xbfb8aa3b, v153
	v_pk_mul_f32 v[90:91], v[82:83], v[88:89] op_sel_hi:[1,0]
	v_pk_mul_f32 v[82:83], v[84:85], v[88:89] op_sel_hi:[1,0]
	v_exp_f32_e32 v90, v90
	v_exp_f32_e32 v91, v91
	v_exp_f32_e32 v82, v82
	v_exp_f32_e32 v83, v83
	v_cvt_pk_bf16_f32 v97, v86, v87
	v_pk_add_f32 v[90:91], v[90:91], 1.0 op_sel_hi:[1,0]
	v_mad_i64_i32 v[86:87], s[26:27], v152, s1, v[118:119]
	v_rcp_f32_e32 v90, v90
	v_rcp_f32_e32 v91, v91
	v_pk_add_f32 v[82:83], v[82:83], 1.0 op_sel_hi:[1,0]
	v_lshl_add_u64 v[86:87], v[86:87], 0, v[120:121]
	v_rcp_f32_e32 v82, v82
	v_rcp_f32_e32 v83, v83
	global_store_dwordx4 v[86:87], v[94:97], off
	v_mul_f32_e32 v86, v153, v153
	v_pk_mul_f32 v[80:81], v[84:85], v[80:81]
	v_pk_mul_f32 v[84:85], v[86:87], v[90:91] op_sel_hi:[0,1]
	v_pk_mul_f32 v[78:79], v[78:79], v[84:85]
	v_pk_mul_f32 v[84:85], v[74:75], v[88:89] op_sel_hi:[1,0]
	v_pk_mul_f32 v[82:83], v[86:87], v[82:83] op_sel_hi:[0,1]
	v_exp_f32_e32 v84, v84
	v_exp_f32_e32 v85, v85
	v_pk_mul_f32 v[80:81], v[80:81], v[82:83]
	v_pk_mul_f32 v[82:83], v[76:77], v[88:89] op_sel_hi:[1,0]
	v_cvt_pk_bf16_f32 v78, v78, v79
	v_exp_f32_e32 v82, v82
	v_exp_f32_e32 v83, v83
	v_cvt_pk_bf16_f32 v79, v80, v81
	v_pk_add_f32 v[80:81], v[84:85], 1.0 op_sel_hi:[1,0]
	v_pk_mul_f32 v[70:71], v[74:75], v[70:71]
	v_rcp_f32_e32 v80, v80
	v_rcp_f32_e32 v81, v81
	v_pk_add_f32 v[74:75], v[82:83], 1.0 op_sel_hi:[1,0]
	v_pk_mul_f32 v[72:73], v[76:77], v[72:73]
	v_rcp_f32_e32 v74, v74
	v_rcp_f32_e32 v75, v75
	v_pk_mul_f32 v[76:77], v[86:87], v[80:81] op_sel_hi:[0,1]
	v_pk_mul_f32 v[70:71], v[70:71], v[76:77]
	v_pk_mul_f32 v[62:63], v[66:67], v[62:63]
	v_cvt_pk_bf16_f32 v80, v70, v71
	v_pk_mul_f32 v[70:71], v[86:87], v[74:75] op_sel_hi:[0,1]
	v_pk_mul_f32 v[70:71], v[72:73], v[70:71]
	v_mul_f32_e32 v72, 0xbfb8aa3b, v155
	v_pk_mul_f32 v[74:75], v[66:67], v[72:73] op_sel_hi:[1,0]
	v_pk_mul_f32 v[66:67], v[68:69], v[72:73] op_sel_hi:[1,0]
	v_exp_f32_e32 v74, v74
	v_exp_f32_e32 v75, v75
	v_exp_f32_e32 v66, v66
	v_exp_f32_e32 v67, v67
	v_cvt_pk_bf16_f32 v81, v70, v71
	v_pk_add_f32 v[74:75], v[74:75], 1.0 op_sel_hi:[1,0]
	v_mad_i64_i32 v[70:71], s[26:27], v150, s1, v[118:119]
	v_rcp_f32_e32 v74, v74
	v_rcp_f32_e32 v75, v75
	v_pk_add_f32 v[66:67], v[66:67], 1.0 op_sel_hi:[1,0]
	v_lshl_add_u64 v[70:71], v[70:71], 0, v[120:121]
	v_rcp_f32_e32 v66, v66
	v_rcp_f32_e32 v67, v67
	global_store_dwordx4 v[70:71], v[78:81], off
	v_mul_f32_e32 v70, v155, v155
	v_pk_mul_f32 v[64:65], v[68:69], v[64:65]
	v_pk_mul_f32 v[68:69], v[70:71], v[74:75] op_sel_hi:[0,1]
	v_pk_mul_f32 v[62:63], v[62:63], v[68:69]
	v_pk_mul_f32 v[68:69], v[58:59], v[72:73] op_sel_hi:[1,0]
	v_pk_mul_f32 v[66:67], v[70:71], v[66:67] op_sel_hi:[0,1]
	v_exp_f32_e32 v68, v68
	v_exp_f32_e32 v69, v69
	v_pk_mul_f32 v[64:65], v[64:65], v[66:67]
	v_pk_mul_f32 v[66:67], v[60:61], v[72:73] op_sel_hi:[1,0]
	v_cvt_pk_bf16_f32 v62, v62, v63
	v_exp_f32_e32 v66, v66
	v_exp_f32_e32 v67, v67
	v_cvt_pk_bf16_f32 v63, v64, v65
	v_pk_add_f32 v[64:65], v[68:69], 1.0 op_sel_hi:[1,0]
	v_pk_mul_f32 v[54:55], v[58:59], v[54:55]
	v_rcp_f32_e32 v64, v64
	v_rcp_f32_e32 v65, v65
	v_pk_add_f32 v[58:59], v[66:67], 1.0 op_sel_hi:[1,0]
	v_pk_mul_f32 v[56:57], v[60:61], v[56:57]
	v_rcp_f32_e32 v58, v58
	v_rcp_f32_e32 v59, v59
	v_pk_mul_f32 v[60:61], v[70:71], v[64:65] op_sel_hi:[0,1]
	v_pk_mul_f32 v[54:55], v[54:55], v[60:61]
	v_pk_mul_f32 v[46:47], v[50:51], v[46:47]
	v_cvt_pk_bf16_f32 v64, v54, v55
	v_pk_mul_f32 v[54:55], v[70:71], v[58:59] op_sel_hi:[0,1]
	v_pk_mul_f32 v[54:55], v[56:57], v[54:55]
	v_mul_f32_e32 v56, 0xbfb8aa3b, v157
	v_pk_mul_f32 v[58:59], v[50:51], v[56:57] op_sel_hi:[1,0]
	v_pk_mul_f32 v[50:51], v[52:53], v[56:57] op_sel_hi:[1,0]
	v_exp_f32_e32 v58, v58
	v_exp_f32_e32 v59, v59
	v_exp_f32_e32 v50, v50
	v_exp_f32_e32 v51, v51
	v_cvt_pk_bf16_f32 v65, v54, v55
	v_pk_add_f32 v[58:59], v[58:59], 1.0 op_sel_hi:[1,0]
	v_mad_i64_i32 v[54:55], s[26:27], v148, s1, v[118:119]
	v_rcp_f32_e32 v58, v58
	v_rcp_f32_e32 v59, v59
	v_pk_add_f32 v[50:51], v[50:51], 1.0 op_sel_hi:[1,0]
	v_lshl_add_u64 v[54:55], v[54:55], 0, v[120:121]
	v_rcp_f32_e32 v50, v50
	v_rcp_f32_e32 v51, v51
	global_store_dwordx4 v[54:55], v[62:65], off
	v_mul_f32_e32 v54, v157, v157
	v_pk_mul_f32 v[48:49], v[52:53], v[48:49]
	v_pk_mul_f32 v[52:53], v[54:55], v[58:59] op_sel_hi:[0,1]
	v_pk_mul_f32 v[46:47], v[46:47], v[52:53]
	v_pk_mul_f32 v[52:53], v[42:43], v[56:57] op_sel_hi:[1,0]
	v_pk_mul_f32 v[50:51], v[54:55], v[50:51] op_sel_hi:[0,1]
	v_exp_f32_e32 v52, v52
	v_exp_f32_e32 v53, v53
	v_pk_mul_f32 v[48:49], v[48:49], v[50:51]
; __device__ __forceinline__ unsigned pk2(float lo, float hi) { const f32x2 v = {lo, hi}; return __builtin_bit_cast(unsigned, __builtin_convertvector(v, bf16x2_t)); }
;     __device__ __forceinline__ void operator()(const f32x4 (&acc)[2][2][4][2], const Unit& u, int wr, int wc, int fr, int fq) const {
;     ...
; #pragma unroll
;         for (int ai = 0; ai < 2; ++ai)
; #pragma unroll
;             for (int m = 0; m < 4; ++m) {
;                 const float rs = rs8[ai][m], nrs = -1.44269504089f * rs;
;                 u32x4 w;
; #pragma unroll
;                 for (int n = 0; n < 2; ++n) { const f32x4 gq = acc[ai][0][m][n], uq = acc[ai][1][m][n];
; #pragma unroll
;                     for (int h = 0; h < 2; ++h) { const f32x2 gv = (f32x2){gq[2 * h], gq[2 * h + 1]}, uv = (f32x2){uq[2 * h], uq[2 * h + 1]};
;                         const f32x2 ea = gv * nrs; f32x2 e; e.x = __builtin_amdgcn_exp2f(ea.x); e.y = __builtin_amdgcn_exp2f(ea.y);
;                         const f32x2 d = e + 1.0f; f32x2 rc; rc.x = __builtin_amdgcn_rcpf(d.x); rc.y = __builtin_amdgcn_rcpf(d.y);
;                         const f32x2 o = (gv * uv) * (rc * (rs * rs));
;                         w[2 * n + h] = pk2(o.x, o.y); } }
;                 *(u32x4*)(O + (size_t)(row0 + ai * HALF + m * 16) * ldc + col0) = w; }
	v_pk_mul_f32 v[50:51], v[44:45], v[56:57] op_sel_hi:[1,0]
	v_cvt_pk_bf16_f32 v46, v46, v47
	v_exp_f32_e32 v50, v50
	v_exp_f32_e32 v51, v51
	v_cvt_pk_bf16_f32 v47, v48, v49
	v_pk_add_f32 v[48:49], v[52:53], 1.0 op_sel_hi:[1,0]
	v_pk_mul_f32 v[38:39], v[42:43], v[38:39]
	v_rcp_f32_e32 v48, v48
	v_rcp_f32_e32 v49, v49
	v_pk_add_f32 v[42:43], v[50:51], 1.0 op_sel_hi:[1,0]
	v_pk_mul_f32 v[40:41], v[44:45], v[40:41]
	v_rcp_f32_e32 v42, v42
	v_rcp_f32_e32 v43, v43
	v_pk_mul_f32 v[44:45], v[54:55], v[48:49] op_sel_hi:[0,1]
	v_pk_mul_f32 v[38:39], v[38:39], v[44:45]
	v_pk_mul_f32 v[30:31], v[34:35], v[30:31]
	v_cvt_pk_bf16_f32 v48, v38, v39
	v_pk_mul_f32 v[38:39], v[54:55], v[42:43] op_sel_hi:[0,1]
	v_pk_mul_f32 v[38:39], v[40:41], v[38:39]
	v_mul_f32_e32 v40, 0xbfb8aa3b, v145
	v_pk_mul_f32 v[42:43], v[34:35], v[40:41] op_sel_hi:[1,0]
	v_pk_mul_f32 v[34:35], v[36:37], v[40:41] op_sel_hi:[1,0]
	v_exp_f32_e32 v42, v42
	v_exp_f32_e32 v43, v43
	v_exp_f32_e32 v34, v34
	v_exp_f32_e32 v35, v35
	v_cvt_pk_bf16_f32 v49, v38, v39
	v_pk_add_f32 v[42:43], v[42:43], 1.0 op_sel_hi:[1,0]
	v_mad_i64_i32 v[38:39], s[26:27], v146, s1, v[118:119]
	v_rcp_f32_e32 v42, v42
	v_rcp_f32_e32 v43, v43
	v_pk_add_f32 v[34:35], v[34:35], 1.0 op_sel_hi:[1,0]
	v_lshl_add_u64 v[38:39], v[38:39], 0, v[120:121]
	v_rcp_f32_e32 v34, v34
	v_rcp_f32_e32 v35, v35
	global_store_dwordx4 v[38:39], v[46:49], off
	v_mul_f32_e32 v38, v145, v145
	v_pk_mul_f32 v[32:33], v[36:37], v[32:33]
	v_pk_mul_f32 v[36:37], v[38:39], v[42:43] op_sel_hi:[0,1]
	v_pk_mul_f32 v[30:31], v[30:31], v[36:37]
	v_pk_mul_f32 v[36:37], v[26:27], v[40:41] op_sel_hi:[1,0]
	v_pk_mul_f32 v[34:35], v[38:39], v[34:35] op_sel_hi:[0,1]
	v_exp_f32_e32 v36, v36
	v_exp_f32_e32 v37, v37
	v_pk_mul_f32 v[32:33], v[32:33], v[34:35]
	v_pk_mul_f32 v[34:35], v[28:29], v[40:41] op_sel_hi:[1,0]
	v_cvt_pk_bf16_f32 v30, v30, v31
	v_exp_f32_e32 v34, v34
	v_exp_f32_e32 v35, v35
	v_cvt_pk_bf16_f32 v31, v32, v33
	v_pk_add_f32 v[32:33], v[36:37], 1.0 op_sel_hi:[1,0]
	v_pk_mul_f32 v[22:23], v[26:27], v[22:23]
	v_rcp_f32_e32 v32, v32
	v_rcp_f32_e32 v33, v33
	v_pk_add_f32 v[26:27], v[34:35], 1.0 op_sel_hi:[1,0]
	v_pk_mul_f32 v[24:25], v[28:29], v[24:25]
	v_rcp_f32_e32 v26, v26
	v_rcp_f32_e32 v27, v27
	v_pk_mul_f32 v[28:29], v[38:39], v[32:33] op_sel_hi:[0,1]
	v_pk_mul_f32 v[22:23], v[22:23], v[28:29]
	v_pk_mul_f32 v[14:15], v[18:19], v[14:15]
	v_cvt_pk_bf16_f32 v32, v22, v23
	v_pk_mul_f32 v[22:23], v[38:39], v[26:27] op_sel_hi:[0,1]
	v_pk_mul_f32 v[22:23], v[24:25], v[22:23]
	v_mul_f32_e32 v24, 0xbfb8aa3b, v143
	v_pk_mul_f32 v[26:27], v[18:19], v[24:25] op_sel_hi:[1,0]
	v_pk_mul_f32 v[18:19], v[20:21], v[24:25] op_sel_hi:[1,0]
	v_exp_f32_e32 v26, v26
	v_exp_f32_e32 v27, v27
	v_exp_f32_e32 v18, v18
	v_exp_f32_e32 v19, v19
	v_cvt_pk_bf16_f32 v33, v22, v23
	v_pk_add_f32 v[26:27], v[26:27], 1.0 op_sel_hi:[1,0]
	v_mad_i64_i32 v[22:23], s[26:27], v144, s1, v[118:119]
	v_rcp_f32_e32 v26, v26
	v_rcp_f32_e32 v27, v27
	v_pk_add_f32 v[18:19], v[18:19], 1.0 op_sel_hi:[1,0]
	v_lshl_add_u64 v[22:23], v[22:23], 0, v[120:121]
	v_rcp_f32_e32 v18, v18
	v_rcp_f32_e32 v19, v19
	global_store_dwordx4 v[22:23], v[30:33], off
	v_mul_f32_e32 v22, v143, v143
	v_pk_mul_f32 v[16:17], v[20:21], v[16:17]
	v_pk_mul_f32 v[20:21], v[22:23], v[26:27] op_sel_hi:[0,1]
	v_pk_mul_f32 v[14:15], v[14:15], v[20:21]
	v_pk_mul_f32 v[20:21], v[10:11], v[24:25] op_sel_hi:[1,0]
	v_pk_mul_f32 v[18:19], v[22:23], v[18:19] op_sel_hi:[0,1]
	v_exp_f32_e32 v20, v20
	v_exp_f32_e32 v21, v21
	v_pk_mul_f32 v[16:17], v[16:17], v[18:19]
	v_pk_mul_f32 v[18:19], v[12:13], v[24:25] op_sel_hi:[1,0]
	v_cvt_pk_bf16_f32 v14, v14, v15
	v_exp_f32_e32 v18, v18
	v_exp_f32_e32 v19, v19
	v_cvt_pk_bf16_f32 v15, v16, v17
	v_pk_add_f32 v[16:17], v[20:21], 1.0 op_sel_hi:[1,0]
	v_pk_mul_f32 v[6:7], v[10:11], v[6:7]
	v_rcp_f32_e32 v16, v16
	v_rcp_f32_e32 v17, v17
	v_pk_add_f32 v[10:11], v[18:19], 1.0 op_sel_hi:[1,0]
	v_pk_mul_f32 v[8:9], v[12:13], v[8:9]
	v_rcp_f32_e32 v10, v10
	v_rcp_f32_e32 v11, v11
	v_pk_mul_f32 v[12:13], v[22:23], v[16:17] op_sel_hi:[0,1]
	v_pk_mul_f32 v[6:7], v[6:7], v[12:13]
	s_andn2_b64 vcc, exec, s[38:39]
	v_cvt_pk_bf16_f32 v16, v6, v7
	v_pk_mul_f32 v[6:7], v[22:23], v[10:11] op_sel_hi:[0,1]
	v_pk_mul_f32 v[6:7], v[8:9], v[6:7]
	s_nop 0
	v_cvt_pk_bf16_f32 v17, v6, v7
	v_mad_i64_i32 v[6:7], s[26:27], v142, s1, v[118:119]
	v_lshl_add_u64 v[6:7], v[6:7], 0, v[120:121]
	s_mov_b64 s[26:27], -1
	global_store_dwordx4 v[6:7], v[14:17], off
	s_cbranch_vccnz .LBB0_133
	s_andn2_b64 vcc, exec, s[10:11]
	s_cbranch_vccnz .LBB0_132
	s_barrier
	s_branch .LBB0_132

; __global__ void __launch_bounds__(512, 2) mk_fwd(Args args) {
	.amdhsa_kernel _Z6mk_fwd4Args
		.amdhsa_group_segment_fixed_size 0
		.amdhsa_private_segment_fixed_size 0
		.amdhsa_kernarg_size 424
		.amdhsa_user_sgpr_count 2
		.amdhsa_user_sgpr_dispatch_ptr 0
		.amdhsa_user_sgpr_queue_ptr 0
		.amdhsa_user_sgpr_kernarg_segment_ptr 1
		.amdhsa_user_sgpr_dispatch_id 0
		.amdhsa_user_sgpr_kernarg_preload_length 0
		.amdhsa_user_sgpr_kernarg_preload_offset 0
		.amdhsa_user_sgpr_private_segment_size 0
		.amdhsa_uses_dynamic_stack 0
		.amdhsa_enable_private_segment 0
		.amdhsa_system_sgpr_workgroup_id_x 1
		.amdhsa_system_sgpr_workgroup_id_y 0
		.amdhsa_system_sgpr_workgroup_id_z 0
		.amdhsa_system_sgpr_workgroup_info 0
		.amdhsa_system_vgpr_workitem_id 0
		.amdhsa_next_free_vgpr 256
		.amdhsa_next_free_sgpr 102
		.amdhsa_accum_offset 256
		.amdhsa_reserve_vcc 1
		.amdhsa_float_round_mode_32 0
		.amdhsa_float_round_mode_16_64 0
		.amdhsa_float_denorm_mode_32 3
		.amdhsa_float_denorm_mode_16_64 3
		.amdhsa_dx10_clamp 1
		.amdhsa_ieee_mode 1
		.amdhsa_fp16_overflow 0
		.amdhsa_tg_split 0
		.amdhsa_exception_fp_ieee_invalid_op 0
		.amdhsa_exception_fp_denorm_src 0
		.amdhsa_exception_fp_ieee_div_zero 0
		.amdhsa_exception_fp_ieee_overflow 0
		.amdhsa_exception_fp_ieee_underflow 0
		.amdhsa_exception_fp_ieee_inexact 0
		.amdhsa_exception_int_div_zero 0
	.end_amdhsa_kernel

; __global__ void __launch_bounds__(512, 2) mk_fwd(Args args) {
amdhsa.kernels:
  - .agpr_count:     0
    .args:
      - .offset:         0
        .size:           168
        .value_kind:     by_value
      - .offset:         168
        .size:           4
        .value_kind:     hidden_block_count_x
      - .offset:         172
        .size:           4
        .value_kind:     hidden_block_count_y
      - .offset:         176
        .size:           4
        .value_kind:     hidden_block_count_z
      - .offset:         180
        .size:           2
        .value_kind:     hidden_group_size_x
      - .offset:         182
        .size:           2
        .value_kind:     hidden_group_size_y
      - .offset:         184
        .size:           2
        .value_kind:     hidden_group_size_z
      - .offset:         186
        .size:           2
        .value_kind:     hidden_remainder_x
      - .offset:         188
        .size:           2
        .value_kind:     hidden_remainder_y
      - .offset:         190
        .size:           2
        .value_kind:     hidden_remainder_z
      - .offset:         208
        .size:           8
        .value_kind:     hidden_global_offset_x
      - .offset:         216
        .size:           8
        .value_kind:     hidden_global_offset_y
      - .offset:         224
        .size:           8
        .value_kind:     hidden_global_offset_z
      - .offset:         232
        .size:           2
        .value_kind:     hidden_grid_dims
      - .offset:         288
        .size:           4
        .value_kind:     hidden_dynamic_lds_size
    .group_segment_fixed_size: 0
    .kernarg_segment_align: 8
    .kernarg_segment_size: 424
    .language:       OpenCL C
    .language_version:
      - 2
      - 0
    .max_flat_workgroup_size: 512
    .name:           _Z6mk_fwd4Args
    .private_segment_fixed_size: 0
    .sgpr_count:     108
    .sgpr_spill_count: 152
    .symbol:         _Z6mk_fwd4Args.kd
    .uniform_work_group_size: 1
    .uses_dynamic_stack: false
    .vgpr_count:     256
    .vgpr_spill_count: 0
    .wavefront_size: 64
